# B-layer weight bf16 copies (written ~0.8 ms before first use) stored with nt so they do not displace the A-layer working set in the Infinity Cache
# baseline (speedup 1.0000x reference)
.LBB0_95:
	s_waitcnt vmcnt(30)
	ds_write2_b32 v53, v14, v15 offset1:66
	s_waitcnt vmcnt(28)
	ds_write2_b32 v53, v18, v19 offset0:132 offset1:198
	v_add_u32_e32 v14, 0x400, v53
	s_waitcnt vmcnt(26)
	ds_write2_b32 v14, v16, v17 offset0:8 offset1:74
	s_waitcnt vmcnt(24)
	ds_write2_b32 v14, v20, v21 offset0:140 offset1:206
	v_add_u32_e32 v14, 0x800, v53
	s_waitcnt vmcnt(22)
	ds_write2_b32 v14, v22, v23 offset0:16 offset1:82
	s_waitcnt vmcnt(20)
	ds_write2_b32 v14, v26, v27 offset0:148 offset1:214
	v_add_u32_e32 v14, 0xc00, v53
	s_waitcnt vmcnt(18)
	ds_write2_b32 v14, v24, v25 offset0:24 offset1:90
	s_waitcnt vmcnt(16)
	ds_write2_b32 v14, v28, v29 offset0:156 offset1:222
	v_add_u32_e32 v14, 0x1000, v53
	s_waitcnt vmcnt(14)
	ds_write2_b32 v14, v30, v31 offset0:32 offset1:98
	s_waitcnt vmcnt(12)
	ds_write2_b32 v14, v34, v35 offset0:164 offset1:230
	v_add_u32_e32 v14, 0x1400, v53
	s_waitcnt vmcnt(10)
	ds_write2_b32 v14, v32, v33 offset0:40 offset1:106
	s_waitcnt vmcnt(8)
	ds_write2_b32 v14, v36, v37 offset0:172 offset1:238
	v_add_u32_e32 v14, 0x1800, v53
	s_waitcnt vmcnt(6)
	ds_write2_b32 v14, v38, v39 offset0:48 offset1:114
	s_waitcnt vmcnt(4)
	ds_write2_b32 v14, v44, v45 offset0:180 offset1:246
	v_add_u32_e32 v14, 0x1c00, v53
	s_waitcnt vmcnt(2)
	ds_write2_b32 v14, v42, v43 offset0:56 offset1:122
	s_waitcnt vmcnt(0)
	ds_write2_b32 v14, v40, v41 offset0:188 offset1:254
	s_waitcnt lgkmcnt(0)
	ds_read2_b32 v[14:15], v51 offset1:33
	s_waitcnt lgkmcnt(0)
	v_cvt_pk_bf16_f32 v14, v14, v15
	ds_read2_b32 v[16:17], v51 offset0:66 offset1:99
	s_waitcnt lgkmcnt(0)
	v_cvt_pk_bf16_f32 v15, v16, v17
	ds_read2_b32 v[16:17], v51 offset0:132 offset1:165
	s_waitcnt lgkmcnt(0)
	v_cvt_pk_bf16_f32 v16, v16, v17
	ds_read2_b32 v[18:19], v51 offset0:198 offset1:231
	v_sub_u32_e32 v22, 0, v55
	s_waitcnt lgkmcnt(0)
	v_cvt_pk_bf16_f32 v17, v18, v19
	v_add3_u32 v18, v48, v9, v22
	v_ashrrev_i32_e32 v19, 31, v18
	v_lshl_add_u64 v[20:21], v[12:13], 1, v[10:11]
	v_lshlrev_b64 v[22:23], 12, v[18:19]
	ds_read2_b32 v[12:13], v51 offset0:8 offset1:41
	v_lshl_add_u64 v[22:23], v[20:21], 0, v[22:23]
	global_store_dwordx4 v[22:23], v[14:17], off nt
	s_waitcnt lgkmcnt(0)
	v_cvt_pk_bf16_f32 v12, v12, v13
	ds_read2_b32 v[14:15], v51 offset0:74 offset1:107
	s_waitcnt lgkmcnt(0)
	v_cvt_pk_bf16_f32 v13, v14, v15
	ds_read2_b32 v[14:15], v51 offset0:140 offset1:173
	s_waitcnt lgkmcnt(0)
	v_cvt_pk_bf16_f32 v14, v14, v15
	ds_read2_b32 v[16:17], v51 offset0:206 offset1:239
	s_waitcnt lgkmcnt(0)
	v_cvt_pk_bf16_f32 v15, v16, v17
	v_add_u32_e32 v16, 8, v18
	v_ashrrev_i32_e32 v17, 31, v16
	v_lshlrev_b64 v[16:17], 12, v[16:17]
	ds_read2_b32 v[22:23], v51 offset0:16 offset1:49
	v_lshl_add_u64 v[16:17], v[20:21], 0, v[16:17]
	global_store_dwordx4 v[16:17], v[12:15], off nt
	v_add_u32_e32 v54, s24, v54
	v_cmp_lt_i32_e32 vcc, s60, v54
	s_waitcnt lgkmcnt(0)
	v_cvt_pk_bf16_f32 v12, v22, v23
	v_add_u32_e32 v22, 16, v18
	ds_read2_b32 v[14:15], v51 offset0:82 offset1:115
	v_ashrrev_i32_e32 v23, 31, v22
	s_waitcnt lgkmcnt(0)
	v_cvt_pk_bf16_f32 v13, v14, v15
	ds_read2_b32 v[14:15], v51 offset0:148 offset1:181
	v_lshlrev_b64 v[22:23], 12, v[22:23]
	v_add_u32_e32 v18, 24, v18
	s_waitcnt lgkmcnt(0)
	v_cvt_pk_bf16_f32 v14, v14, v15
	ds_read2_b32 v[16:17], v51 offset0:214 offset1:247
	s_waitcnt lgkmcnt(0)
	v_cvt_pk_bf16_f32 v15, v16, v17
	v_lshl_add_u64 v[22:23], v[20:21], 0, v[22:23]
	v_ashrrev_i32_e32 v19, 31, v18
	ds_read2_b32 v[16:17], v51 offset0:24 offset1:57
	global_store_dwordx4 v[22:23], v[12:15], off nt
	v_lshlrev_b64 v[18:19], 12, v[18:19]
	v_lshl_add_u64 v[18:19], v[20:21], 0, v[18:19]
	s_waitcnt lgkmcnt(0)
	v_cvt_pk_bf16_f32 v12, v16, v17
	ds_read2_b32 v[14:15], v51 offset0:90 offset1:123
	s_waitcnt lgkmcnt(0)
	v_cvt_pk_bf16_f32 v13, v14, v15
	ds_read2_b32 v[14:15], v51 offset0:156 offset1:189
	s_waitcnt lgkmcnt(0)
	v_cvt_pk_bf16_f32 v14, v14, v15
	ds_read2_b32 v[16:17], v51 offset0:222 offset1:255
	s_waitcnt lgkmcnt(0)
	v_cvt_pk_bf16_f32 v15, v16, v17
	global_store_dwordx4 v[18:19], v[12:15], off nt
	s_waitcnt lgkmcnt(0)
	s_or_b64 s[6:7], vcc, s[6:7]
	v_add_u32_e32 v9, s22, v9
	s_andn2_b64 exec, exec, s[6:7]
	s_cbranch_execz .LBB0_98

.LBB0_99:
	s_waitcnt vmcnt(30)
	ds_write2_b32 v53, v12, v13 offset1:66
	s_waitcnt vmcnt(28)
	ds_write2_b32 v53, v16, v17 offset0:132 offset1:198
	v_add_u32_e32 v12, 0x400, v53
	s_waitcnt vmcnt(26)
	ds_write2_b32 v12, v14, v15 offset0:8 offset1:74
	s_waitcnt vmcnt(24)
	ds_write2_b32 v12, v18, v19 offset0:140 offset1:206
	v_add_u32_e32 v12, 0x800, v53
	s_waitcnt vmcnt(22)
	ds_write2_b32 v12, v20, v21 offset0:16 offset1:82
	s_waitcnt vmcnt(20)
	ds_write2_b32 v12, v24, v25 offset0:148 offset1:214
	v_add_u32_e32 v12, 0xc00, v53
	s_waitcnt vmcnt(18)
	ds_write2_b32 v12, v22, v23 offset0:24 offset1:90
	s_waitcnt vmcnt(16)
	ds_write2_b32 v12, v26, v27 offset0:156 offset1:222
	v_add_u32_e32 v12, 0x1000, v53
	s_waitcnt vmcnt(14)
	ds_write2_b32 v12, v28, v29 offset0:32 offset1:98
	s_waitcnt vmcnt(12)
	ds_write2_b32 v12, v32, v33 offset0:164 offset1:230
	v_add_u32_e32 v12, 0x1400, v53
	s_waitcnt vmcnt(10)
	ds_write2_b32 v12, v30, v31 offset0:40 offset1:106
	s_waitcnt vmcnt(8)
	ds_write2_b32 v12, v34, v35 offset0:172 offset1:238
	v_add_u32_e32 v12, 0x1800, v53
	s_waitcnt vmcnt(6)
	ds_write2_b32 v12, v36, v37 offset0:48 offset1:114
	s_waitcnt vmcnt(4)
	ds_write2_b32 v12, v42, v43 offset0:180 offset1:246
	v_add_u32_e32 v12, 0x1c00, v53
	s_waitcnt vmcnt(2)
	ds_write2_b32 v12, v40, v41 offset0:56 offset1:122
	s_waitcnt vmcnt(0)
	ds_write2_b32 v12, v38, v39 offset0:188 offset1:254
	s_waitcnt lgkmcnt(0)
	ds_read2_b32 v[12:13], v51 offset1:33
	s_waitcnt lgkmcnt(0)
	v_cvt_pk_bf16_f32 v12, v12, v13
	ds_read2_b32 v[14:15], v51 offset0:66 offset1:99
	s_waitcnt lgkmcnt(0)
	v_cvt_pk_bf16_f32 v13, v14, v15
	ds_read2_b32 v[14:15], v51 offset0:132 offset1:165
	s_waitcnt lgkmcnt(0)
	v_cvt_pk_bf16_f32 v14, v14, v15
	ds_read2_b32 v[16:17], v51 offset0:198 offset1:231
	v_sub_u32_e32 v20, 0, v45
	s_waitcnt lgkmcnt(0)
	v_cvt_pk_bf16_f32 v15, v16, v17
	v_add3_u32 v16, v48, v52, v20
	v_ashrrev_i32_e32 v17, 31, v16
	v_lshl_add_u64 v[18:19], v[10:11], 1, v[8:9]
	v_lshlrev_b64 v[20:21], 12, v[16:17]
	ds_read2_b32 v[10:11], v51 offset0:8 offset1:41
	v_lshl_add_u64 v[20:21], v[18:19], 0, v[20:21]
	global_store_dwordx4 v[20:21], v[12:15], off nt
	s_waitcnt lgkmcnt(0)
	v_cvt_pk_bf16_f32 v10, v10, v11
	ds_read2_b32 v[12:13], v51 offset0:74 offset1:107
	s_waitcnt lgkmcnt(0)
	v_cvt_pk_bf16_f32 v11, v12, v13
	ds_read2_b32 v[12:13], v51 offset0:140 offset1:173
	s_waitcnt lgkmcnt(0)
	v_cvt_pk_bf16_f32 v12, v12, v13
	ds_read2_b32 v[14:15], v51 offset0:206 offset1:239
	s_waitcnt lgkmcnt(0)
	v_cvt_pk_bf16_f32 v13, v14, v15
	v_add_u32_e32 v14, 8, v16
	v_ashrrev_i32_e32 v15, 31, v14
	v_lshlrev_b64 v[14:15], 12, v[14:15]
	ds_read2_b32 v[20:21], v51 offset0:16 offset1:49
	v_lshl_add_u64 v[14:15], v[18:19], 0, v[14:15]
	global_store_dwordx4 v[14:15], v[10:13], off nt
	v_add_u32_e32 v44, s24, v44
	v_cmp_lt_i32_e32 vcc, s58, v44
	s_waitcnt lgkmcnt(0)
	v_cvt_pk_bf16_f32 v10, v20, v21
	v_add_u32_e32 v20, 16, v16
	ds_read2_b32 v[12:13], v51 offset0:82 offset1:115
	v_ashrrev_i32_e32 v21, 31, v20
	s_waitcnt lgkmcnt(0)
	v_cvt_pk_bf16_f32 v11, v12, v13
	ds_read2_b32 v[12:13], v51 offset0:148 offset1:181
	v_lshlrev_b64 v[20:21], 12, v[20:21]
	v_add_u32_e32 v16, 24, v16
	s_waitcnt lgkmcnt(0)
	v_cvt_pk_bf16_f32 v12, v12, v13
	ds_read2_b32 v[14:15], v51 offset0:214 offset1:247
	s_waitcnt lgkmcnt(0)
	v_cvt_pk_bf16_f32 v13, v14, v15
	v_lshl_add_u64 v[20:21], v[18:19], 0, v[20:21]
	v_ashrrev_i32_e32 v17, 31, v16
	ds_read2_b32 v[14:15], v51 offset0:24 offset1:57
	global_store_dwordx4 v[20:21], v[10:13], off nt
	v_lshlrev_b64 v[16:17], 12, v[16:17]
	v_lshl_add_u64 v[16:17], v[18:19], 0, v[16:17]
	s_waitcnt lgkmcnt(0)
	v_cvt_pk_bf16_f32 v10, v14, v15
	ds_read2_b32 v[12:13], v51 offset0:90 offset1:123
	s_waitcnt lgkmcnt(0)
	v_cvt_pk_bf16_f32 v11, v12, v13
	ds_read2_b32 v[12:13], v51 offset0:156 offset1:189
	s_waitcnt lgkmcnt(0)
	v_cvt_pk_bf16_f32 v12, v12, v13
	ds_read2_b32 v[14:15], v51 offset0:222 offset1:255
	s_waitcnt lgkmcnt(0)
	v_cvt_pk_bf16_f32 v13, v14, v15
	global_store_dwordx4 v[16:17], v[10:13], off nt
	s_waitcnt lgkmcnt(0)
	s_or_b64 s[6:7], vcc, s[6:7]
	v_add_u32_e32 v52, s22, v52
	s_andn2_b64 exec, exec, s[6:7]
	s_cbranch_execz .LBB0_102

.LBB0_104:
	s_waitcnt vmcnt(30)
	ds_write2_b32 v51, v12, v13 offset1:66
	s_waitcnt vmcnt(28)
	ds_write2_b32 v51, v16, v17 offset0:132 offset1:198
	v_add_u32_e32 v12, 0x400, v51
	s_waitcnt vmcnt(26)
	ds_write2_b32 v12, v14, v15 offset0:8 offset1:74
	s_waitcnt vmcnt(24)
	ds_write2_b32 v12, v18, v19 offset0:140 offset1:206
	v_add_u32_e32 v12, 0x800, v51
	s_waitcnt vmcnt(22)
	ds_write2_b32 v12, v20, v21 offset0:16 offset1:82
	s_waitcnt vmcnt(20)
	ds_write2_b32 v12, v24, v25 offset0:148 offset1:214
	v_add_u32_e32 v12, 0xc00, v51
	s_waitcnt vmcnt(18)
	ds_write2_b32 v12, v22, v23 offset0:24 offset1:90
	s_waitcnt vmcnt(16)
	ds_write2_b32 v12, v26, v27 offset0:156 offset1:222
	v_add_u32_e32 v12, 0x1000, v51
	s_waitcnt vmcnt(14)
	ds_write2_b32 v12, v28, v29 offset0:32 offset1:98
	s_waitcnt vmcnt(12)
	ds_write2_b32 v12, v32, v33 offset0:164 offset1:230
	v_add_u32_e32 v12, 0x1400, v51
	s_waitcnt vmcnt(10)
	ds_write2_b32 v12, v30, v31 offset0:40 offset1:106
	s_waitcnt vmcnt(8)
	ds_write2_b32 v12, v34, v35 offset0:172 offset1:238
	v_add_u32_e32 v12, 0x1800, v51
	s_waitcnt vmcnt(6)
	ds_write2_b32 v12, v36, v37 offset0:48 offset1:114
	s_waitcnt vmcnt(4)
	ds_write2_b32 v12, v42, v43 offset0:180 offset1:246
	v_add_u32_e32 v12, 0x1c00, v51
	s_waitcnt vmcnt(2)
	ds_write2_b32 v12, v40, v41 offset0:56 offset1:122
	s_waitcnt vmcnt(0)
	ds_write2_b32 v12, v38, v39 offset0:188 offset1:254
	s_waitcnt lgkmcnt(0)
	ds_read2_b32 v[12:13], v44 offset1:33
	s_waitcnt lgkmcnt(0)
	v_cvt_pk_bf16_f32 v12, v12, v13
	ds_read2_b32 v[14:15], v44 offset0:66 offset1:99
	s_waitcnt lgkmcnt(0)
	v_cvt_pk_bf16_f32 v13, v14, v15
	ds_read2_b32 v[14:15], v44 offset0:132 offset1:165
	s_waitcnt lgkmcnt(0)
	v_cvt_pk_bf16_f32 v14, v14, v15
	ds_read2_b32 v[16:17], v44 offset0:198 offset1:231
	s_waitcnt lgkmcnt(0)
	v_cvt_pk_bf16_f32 v15, v16, v17
	v_add3_u32 v16, v48, v45, v53
	v_ashrrev_i32_e32 v17, 31, v16
	v_lshl_add_u64 v[18:19], v[10:11], 1, v[8:9]
	v_lshlrev_b64 v[20:21], 12, v[16:17]
	ds_read2_b32 v[10:11], v44 offset0:8 offset1:41
	v_lshl_add_u64 v[20:21], v[18:19], 0, v[20:21]
	global_store_dwordx4 v[20:21], v[12:15], off nt
	s_waitcnt lgkmcnt(0)
	v_cvt_pk_bf16_f32 v10, v10, v11
	ds_read2_b32 v[12:13], v44 offset0:74 offset1:107
	s_waitcnt lgkmcnt(0)
	v_cvt_pk_bf16_f32 v11, v12, v13
	ds_read2_b32 v[12:13], v44 offset0:140 offset1:173
	s_waitcnt lgkmcnt(0)
	v_cvt_pk_bf16_f32 v12, v12, v13
	ds_read2_b32 v[14:15], v44 offset0:206 offset1:239
	s_waitcnt lgkmcnt(0)
	v_cvt_pk_bf16_f32 v13, v14, v15
	v_add_u32_e32 v14, 8, v16
	v_ashrrev_i32_e32 v15, 31, v14
	v_lshlrev_b64 v[14:15], 12, v[14:15]
	ds_read2_b32 v[20:21], v44 offset0:16 offset1:49
	v_lshl_add_u64 v[14:15], v[18:19], 0, v[14:15]
	global_store_dwordx4 v[14:15], v[10:13], off nt
	v_add_u32_e32 v52, s24, v52
	v_cmp_lt_i32_e32 vcc, s60, v52
	s_waitcnt lgkmcnt(0)
	v_cvt_pk_bf16_f32 v10, v20, v21
	v_add_u32_e32 v20, 16, v16
	ds_read2_b32 v[12:13], v44 offset0:82 offset1:115
	v_ashrrev_i32_e32 v21, 31, v20
	s_waitcnt lgkmcnt(0)
	v_cvt_pk_bf16_f32 v11, v12, v13
	ds_read2_b32 v[12:13], v44 offset0:148 offset1:181
	v_lshlrev_b64 v[20:21], 12, v[20:21]
	v_add_u32_e32 v16, 24, v16
	s_waitcnt lgkmcnt(0)
	v_cvt_pk_bf16_f32 v12, v12, v13
	ds_read2_b32 v[14:15], v44 offset0:214 offset1:247
	s_waitcnt lgkmcnt(0)
	v_cvt_pk_bf16_f32 v13, v14, v15
	v_lshl_add_u64 v[20:21], v[18:19], 0, v[20:21]
	v_ashrrev_i32_e32 v17, 31, v16
	ds_read2_b32 v[14:15], v44 offset0:24 offset1:57
	global_store_dwordx4 v[20:21], v[10:13], off nt
	v_lshlrev_b64 v[16:17], 12, v[16:17]
	v_lshl_add_u64 v[16:17], v[18:19], 0, v[16:17]
	s_waitcnt lgkmcnt(0)
	v_cvt_pk_bf16_f32 v10, v14, v15
	ds_read2_b32 v[12:13], v44 offset0:90 offset1:123
	s_waitcnt lgkmcnt(0)
	v_cvt_pk_bf16_f32 v11, v12, v13
	ds_read2_b32 v[12:13], v44 offset0:156 offset1:189
	s_waitcnt lgkmcnt(0)
	v_cvt_pk_bf16_f32 v12, v12, v13
	ds_read2_b32 v[14:15], v44 offset0:222 offset1:255
	s_waitcnt lgkmcnt(0)
	v_cvt_pk_bf16_f32 v13, v14, v15
	global_store_dwordx4 v[16:17], v[10:13], off nt
	s_waitcnt lgkmcnt(0)
	s_or_b64 s[8:9], vcc, s[8:9]
	v_add_u32_e32 v45, s22, v45
	s_andn2_b64 exec, exec, s[8:9]
	s_cbranch_execz .LBB0_107

.LBB0_109:
	s_waitcnt vmcnt(30)
	ds_write2_b32 v52, v14, v15 offset1:66
	s_waitcnt vmcnt(28)
	ds_write2_b32 v52, v18, v19 offset0:132 offset1:198
	v_add_u32_e32 v14, 0x400, v52
	s_waitcnt vmcnt(26)
	ds_write2_b32 v14, v16, v17 offset0:8 offset1:74
	s_waitcnt vmcnt(24)
	ds_write2_b32 v14, v20, v21 offset0:140 offset1:206
	v_add_u32_e32 v14, 0x800, v52
	s_waitcnt vmcnt(22)
	ds_write2_b32 v14, v22, v23 offset0:16 offset1:82
	s_waitcnt vmcnt(20)
	ds_write2_b32 v14, v26, v27 offset0:148 offset1:214
	v_add_u32_e32 v14, 0xc00, v52
	s_waitcnt vmcnt(18)
	ds_write2_b32 v14, v24, v25 offset0:24 offset1:90
	s_waitcnt vmcnt(16)
	ds_write2_b32 v14, v28, v29 offset0:156 offset1:222
	v_add_u32_e32 v14, 0x1000, v52
	s_waitcnt vmcnt(14)
	ds_write2_b32 v14, v30, v31 offset0:32 offset1:98
	s_waitcnt vmcnt(12)
	ds_write2_b32 v14, v34, v35 offset0:164 offset1:230
	v_add_u32_e32 v14, 0x1400, v52
	s_waitcnt vmcnt(10)
	ds_write2_b32 v14, v32, v33 offset0:40 offset1:106
	s_waitcnt vmcnt(8)
	ds_write2_b32 v14, v36, v37 offset0:172 offset1:238
	v_add_u32_e32 v14, 0x1800, v52
	s_waitcnt vmcnt(6)
	ds_write2_b32 v14, v38, v39 offset0:48 offset1:114
	s_waitcnt vmcnt(4)
	ds_write2_b32 v14, v44, v45 offset0:180 offset1:246
	v_add_u32_e32 v14, 0x1c00, v52
	s_waitcnt vmcnt(2)
	ds_write2_b32 v14, v42, v43 offset0:56 offset1:122
	s_waitcnt vmcnt(0)
	ds_write2_b32 v14, v40, v41 offset0:188 offset1:254
	s_waitcnt lgkmcnt(0)
	ds_read2_b32 v[14:15], v9 offset1:33
	s_waitcnt lgkmcnt(0)
	v_cvt_pk_bf16_f32 v14, v14, v15
	ds_read2_b32 v[16:17], v9 offset0:66 offset1:99
	s_waitcnt lgkmcnt(0)
	v_cvt_pk_bf16_f32 v15, v16, v17
	ds_read2_b32 v[16:17], v9 offset0:132 offset1:165
	s_waitcnt lgkmcnt(0)
	v_cvt_pk_bf16_f32 v16, v16, v17
	ds_read2_b32 v[18:19], v9 offset0:198 offset1:231
	v_sub_u32_e32 v22, 0, v55
	s_waitcnt lgkmcnt(0)
	v_cvt_pk_bf16_f32 v17, v18, v19
	v_add3_u32 v18, v48, v53, v22
	v_ashrrev_i32_e32 v19, 31, v18
	v_lshl_add_u64 v[20:21], v[12:13], 1, v[10:11]
	v_lshlrev_b64 v[22:23], 12, v[18:19]
	ds_read2_b32 v[12:13], v9 offset0:8 offset1:41
	v_lshl_add_u64 v[22:23], v[20:21], 0, v[22:23]
	global_store_dwordx4 v[22:23], v[14:17], off nt
	s_waitcnt lgkmcnt(0)
	v_cvt_pk_bf16_f32 v12, v12, v13
	ds_read2_b32 v[14:15], v9 offset0:74 offset1:107
	s_waitcnt lgkmcnt(0)
	v_cvt_pk_bf16_f32 v13, v14, v15
	ds_read2_b32 v[14:15], v9 offset0:140 offset1:173
	s_waitcnt lgkmcnt(0)
	v_cvt_pk_bf16_f32 v14, v14, v15
	ds_read2_b32 v[16:17], v9 offset0:206 offset1:239
	s_waitcnt lgkmcnt(0)
	v_cvt_pk_bf16_f32 v15, v16, v17
	v_add_u32_e32 v16, 8, v18
	v_ashrrev_i32_e32 v17, 31, v16
	v_lshlrev_b64 v[16:17], 12, v[16:17]
	ds_read2_b32 v[22:23], v9 offset0:16 offset1:49
	v_lshl_add_u64 v[16:17], v[20:21], 0, v[16:17]
	global_store_dwordx4 v[16:17], v[12:15], off nt
	v_add_u32_e32 v54, s24, v54
	v_cmp_lt_i32_e32 vcc, s59, v54
	s_waitcnt lgkmcnt(0)
	v_cvt_pk_bf16_f32 v12, v22, v23
	v_add_u32_e32 v22, 16, v18
	ds_read2_b32 v[14:15], v9 offset0:82 offset1:115
	v_ashrrev_i32_e32 v23, 31, v22
	s_waitcnt lgkmcnt(0)
	v_cvt_pk_bf16_f32 v13, v14, v15
	ds_read2_b32 v[14:15], v9 offset0:148 offset1:181
	v_lshlrev_b64 v[22:23], 12, v[22:23]
	v_add_u32_e32 v18, 24, v18
	s_waitcnt lgkmcnt(0)
	v_cvt_pk_bf16_f32 v14, v14, v15
	ds_read2_b32 v[16:17], v9 offset0:214 offset1:247
	s_waitcnt lgkmcnt(0)
	v_cvt_pk_bf16_f32 v15, v16, v17
	v_lshl_add_u64 v[22:23], v[20:21], 0, v[22:23]
	v_ashrrev_i32_e32 v19, 31, v18
	ds_read2_b32 v[16:17], v9 offset0:24 offset1:57
	global_store_dwordx4 v[22:23], v[12:15], off nt
	v_lshlrev_b64 v[18:19], 12, v[18:19]
	v_lshl_add_u64 v[18:19], v[20:21], 0, v[18:19]
	s_waitcnt lgkmcnt(0)
	v_cvt_pk_bf16_f32 v12, v16, v17
	ds_read2_b32 v[14:15], v9 offset0:90 offset1:123
	s_waitcnt lgkmcnt(0)
	v_cvt_pk_bf16_f32 v13, v14, v15
	ds_read2_b32 v[14:15], v9 offset0:156 offset1:189
	s_waitcnt lgkmcnt(0)
	v_cvt_pk_bf16_f32 v14, v14, v15
	ds_read2_b32 v[16:17], v9 offset0:222 offset1:255
	s_waitcnt lgkmcnt(0)
	v_cvt_pk_bf16_f32 v15, v16, v17
	global_store_dwordx4 v[18:19], v[12:15], off nt
	s_waitcnt lgkmcnt(0)
	s_or_b64 s[8:9], vcc, s[8:9]
	v_add_u32_e32 v53, s22, v53
	s_andn2_b64 exec, exec, s[8:9]
	s_cbranch_execz .LBB0_112

.LBB0_113:
	v_ashrrev_i32_e32 v14, 31, v13
	v_lshrrev_b32_e32 v14, 26, v14
	v_add_u32_e32 v14, v13, v14
	v_lshlrev_b32_e32 v15, 5, v14
	v_and_b32_e32 v14, 0xffffffc0, v14
	v_or_b32_e32 v16, v14, v47
	v_and_b32_e32 v15, 0xfffff800, v15
	v_ashrrev_i32_e32 v17, 31, v16
	v_sub_u32_e32 v18, v51, v15
	v_lshlrev_b64 v[16:17], 13, v[16:17]
	v_ashrrev_i32_e32 v19, 31, v18
	v_lshl_add_u64 v[16:17], s[14:15], 0, v[16:17]
	v_lshl_add_u64 v[16:17], v[18:19], 2, v[16:17]
	v_lshl_add_u64 v[16:17], v[16:17], 0, v[4:5]
	v_add_co_u32_e32 v20, vcc, s8, v16
	v_ashrrev_i32_e32 v15, 31, v14
	s_nop 0
	v_addc_co_u32_e32 v21, vcc, 0, v17, vcc
	v_add_co_u32_e32 v22, vcc, s9, v16
	v_add_u32_e32 v18, v18, v48
	s_nop 0
	v_addc_co_u32_e32 v23, vcc, 0, v17, vcc
	v_add_co_u32_e32 v24, vcc, s23, v16
	v_ashrrev_i32_e32 v19, 31, v18
	s_nop 0
	v_addc_co_u32_e32 v25, vcc, 0, v17, vcc
	v_add_co_u32_e32 v26, vcc, s25, v16
	v_add_u32_e32 v13, s24, v13
	s_nop 0
	v_addc_co_u32_e32 v27, vcc, 0, v17, vcc
	v_add_co_u32_e32 v28, vcc, s26, v16
	v_add_u32_e32 v51, s22, v51
	s_nop 0
	v_addc_co_u32_e32 v29, vcc, 0, v17, vcc
	v_add_co_u32_e32 v30, vcc, s27, v16
	s_nop 1
	v_addc_co_u32_e32 v31, vcc, 0, v17, vcc
	v_add_co_u32_e32 v32, vcc, s28, v16
	s_nop 1
	v_addc_co_u32_e32 v33, vcc, 0, v17, vcc
	v_add_co_u32_e32 v34, vcc, s29, v16
	s_nop 1
	v_addc_co_u32_e32 v35, vcc, 0, v17, vcc
	v_add_co_u32_e32 v36, vcc, s30, v16
	s_nop 1
	v_addc_co_u32_e32 v37, vcc, 0, v17, vcc
	v_add_co_u32_e32 v38, vcc, s31, v16
	s_nop 1
	v_addc_co_u32_e32 v39, vcc, 0, v17, vcc
	v_add_co_u32_e32 v40, vcc, s34, v16
	s_nop 1
	v_addc_co_u32_e32 v41, vcc, 0, v17, vcc
	v_add_co_u32_e32 v42, vcc, s35, v16
	s_nop 1
	v_addc_co_u32_e32 v43, vcc, 0, v17, vcc
	v_add_co_u32_e32 v44, vcc, s36, v16
	s_nop 1
	v_addc_co_u32_e32 v45, vcc, 0, v17, vcc
	v_add_co_u32_e32 v54, vcc, s37, v16
	s_nop 1
	v_addc_co_u32_e32 v55, vcc, 0, v17, vcc
	v_add_co_u32_e32 v56, vcc, s38, v16
	s_nop 1
	v_addc_co_u32_e32 v57, vcc, 0, v17, vcc
	v_add_co_u32_e32 v58, vcc, s39, v16
	s_nop 1
	v_addc_co_u32_e32 v59, vcc, 0, v17, vcc
	v_add_co_u32_e32 v60, vcc, s40, v16
	s_nop 1
	v_addc_co_u32_e32 v61, vcc, 0, v17, vcc
	v_add_co_u32_e32 v62, vcc, s41, v16
	s_nop 1
	v_addc_co_u32_e32 v63, vcc, 0, v17, vcc
	v_add_co_u32_e32 v64, vcc, s42, v16
	s_nop 1
	v_addc_co_u32_e32 v65, vcc, 0, v17, vcc
	v_add_co_u32_e32 v66, vcc, s43, v16
	s_nop 1
	v_addc_co_u32_e32 v67, vcc, 0, v17, vcc
	v_add_co_u32_e32 v68, vcc, s46, v16
	s_nop 1
	v_addc_co_u32_e32 v69, vcc, 0, v17, vcc
	v_add_co_u32_e32 v70, vcc, s47, v16
	s_nop 1
	v_addc_co_u32_e32 v71, vcc, 0, v17, vcc
	v_add_co_u32_e32 v72, vcc, s48, v16
	s_nop 1
	v_addc_co_u32_e32 v73, vcc, 0, v17, vcc
	v_add_co_u32_e32 v74, vcc, s49, v16
	s_nop 1
	v_addc_co_u32_e32 v75, vcc, 0, v17, vcc
	v_add_co_u32_e32 v76, vcc, s50, v16
	s_nop 1
	v_addc_co_u32_e32 v77, vcc, 0, v17, vcc
	v_add_co_u32_e32 v78, vcc, s51, v16
	s_nop 1
	v_addc_co_u32_e32 v79, vcc, 0, v17, vcc
	v_add_co_u32_e32 v80, vcc, s54, v16
	s_nop 1
	v_addc_co_u32_e32 v81, vcc, 0, v17, vcc
	v_add_co_u32_e32 v82, vcc, s55, v16
	s_nop 1
	v_addc_co_u32_e32 v83, vcc, 0, v17, vcc
	v_add_co_u32_e32 v84, vcc, s56, v16
	s_nop 1
	v_addc_co_u32_e32 v85, vcc, 0, v17, vcc
	v_add_co_u32_e32 v86, vcc, s57, v16
	s_nop 1
	v_addc_co_u32_e32 v87, vcc, 0, v17, vcc
	v_add_co_u32_e32 v88, vcc, s58, v16
	s_nop 1
	v_addc_co_u32_e32 v89, vcc, 0, v17, vcc
	global_load_dword v53, v[16:17], off nt
	global_load_dword v90, v[20:21], off nt
	global_load_dword v91, v[22:23], off nt
	global_load_dword v92, v[24:25], off nt
	global_load_dword v93, v[26:27], off nt
	s_nop 0
	global_load_dword v28, v[28:29], off nt
	s_nop 0
	global_load_dword v29, v[30:31], off nt
	s_nop 0
	global_load_dword v30, v[32:33], off nt
	global_load_dword v31, v[34:35], off nt
	s_nop 0
	global_load_dword v32, v[36:37], off nt
	global_load_dword v33, v[38:39], off nt
	global_load_dword v34, v[40:41], off nt
	global_load_dword v35, v[42:43], off nt
	s_nop 0
	global_load_dword v36, v[44:45], off nt
	global_load_dword v37, v[54:55], off nt
	global_load_dword v38, v[56:57], off nt
	global_load_dword v39, v[58:59], off nt
	global_load_dword v40, v[60:61], off nt
	global_load_dword v41, v[62:63], off nt
	global_load_dword v42, v[64:65], off nt
	global_load_dword v43, v[66:67], off nt
	global_load_dword v44, v[68:69], off nt
	global_load_dword v45, v[70:71], off nt
	global_load_dword v54, v[72:73], off nt
	global_load_dword v55, v[74:75], off nt
	global_load_dword v56, v[76:77], off nt
	global_load_dword v57, v[78:79], off nt
	global_load_dword v58, v[80:81], off nt
	global_load_dword v59, v[82:83], off nt
	global_load_dword v60, v[84:85], off nt
	global_load_dword v61, v[86:87], off nt
	global_load_dword v62, v[88:89], off nt
	v_lshl_add_u64 v[20:21], v[14:15], 1, v[6:7]
	v_add_u32_e32 v14, 8, v18
	v_add_u32_e32 v63, 0x1400, v52
	v_add_u32_e32 v64, 0x1800, v52
	v_add_u32_e32 v65, 0x1c00, v52
	v_add_u32_e32 v16, 16, v18
	v_ashrrev_i32_e32 v15, 31, v14
	s_waitcnt vmcnt(30)
	ds_write2_b32 v52, v53, v90 offset1:66
	s_waitcnt vmcnt(28)
	ds_write2_b32 v52, v91, v92 offset0:132 offset1:198
	s_waitcnt vmcnt(26)
	ds_write2_b32 v8, v93, v28 offset0:8 offset1:74
	s_waitcnt vmcnt(24)
	ds_write2_b32 v8, v29, v30 offset0:140 offset1:206
	s_waitcnt vmcnt(22)
	ds_write2_b32 v10, v31, v32 offset0:16 offset1:82
	s_waitcnt vmcnt(20)
	ds_write2_b32 v10, v33, v34 offset0:148 offset1:214
	s_waitcnt vmcnt(18)
	ds_write2_b32 v11, v35, v36 offset0:24 offset1:90
	s_waitcnt vmcnt(16)
	ds_write2_b32 v11, v37, v38 offset0:156 offset1:222
	s_waitcnt vmcnt(14)
	ds_write2_b32 v12, v39, v40 offset0:32 offset1:98
	s_waitcnt vmcnt(12)
	ds_write2_b32 v12, v41, v42 offset0:164 offset1:230
	s_waitcnt vmcnt(10)
	ds_write2_b32 v63, v43, v44 offset0:40 offset1:106
	s_waitcnt vmcnt(8)
	ds_write2_b32 v63, v45, v54 offset0:172 offset1:238
	s_waitcnt vmcnt(6)
	ds_write2_b32 v64, v55, v56 offset0:48 offset1:114
	s_waitcnt vmcnt(4)
	ds_write2_b32 v64, v57, v58 offset0:180 offset1:246
	s_waitcnt vmcnt(2)
	ds_write2_b32 v65, v59, v60 offset0:56 offset1:122
	s_waitcnt vmcnt(0)
	ds_write2_b32 v65, v61, v62 offset0:188 offset1:254
	v_ashrrev_i32_e32 v17, 31, v16
	v_lshlrev_b64 v[14:15], 12, v[14:15]
	s_waitcnt lgkmcnt(0)
	v_lshlrev_b64 v[16:17], 12, v[16:17]
	v_lshl_add_u64 v[24:25], v[20:21], 0, v[14:15]
	ds_read2_b32 v[14:15], v9 offset1:33
	v_lshl_add_u64 v[26:27], v[20:21], 0, v[16:17]
	s_waitcnt lgkmcnt(0)
	v_cvt_pk_bf16_f32 v14, v14, v15
	ds_read2_b32 v[16:17], v9 offset0:66 offset1:99
	v_lshlrev_b64 v[22:23], 12, v[18:19]
	s_waitcnt lgkmcnt(0)
	v_cvt_pk_bf16_f32 v15, v16, v17
	ds_read2_b32 v[16:17], v9 offset0:132 offset1:165
	v_lshl_add_u64 v[22:23], v[20:21], 0, v[22:23]
	s_waitcnt lgkmcnt(0)
	v_cvt_pk_bf16_f32 v16, v16, v17
	ds_read2_b32 v[28:29], v9 offset0:198 offset1:231
	s_waitcnt lgkmcnt(0)
	v_cvt_pk_bf16_f32 v17, v28, v29
	ds_read2_b32 v[28:29], v9 offset0:8 offset1:41
	global_store_dwordx4 v[22:23], v[14:17], off nt
	v_add_u32_e32 v18, 24, v18
	v_ashrrev_i32_e32 v19, 31, v18
	s_waitcnt lgkmcnt(0)
	v_cvt_pk_bf16_f32 v14, v28, v29
	ds_read2_b32 v[16:17], v9 offset0:74 offset1:107
	s_waitcnt lgkmcnt(0)
	v_cvt_pk_bf16_f32 v15, v16, v17
	ds_read2_b32 v[16:17], v9 offset0:140 offset1:173
	s_waitcnt lgkmcnt(0)
	v_cvt_pk_bf16_f32 v16, v16, v17
	ds_read2_b32 v[22:23], v9 offset0:206 offset1:239
	s_waitcnt lgkmcnt(0)
	v_cvt_pk_bf16_f32 v17, v22, v23
	ds_read2_b32 v[22:23], v9 offset0:16 offset1:49
	global_store_dwordx4 v[24:25], v[14:17], off nt
	v_lshlrev_b64 v[18:19], 12, v[18:19]
	v_lshl_add_u64 v[18:19], v[20:21], 0, v[18:19]
	s_waitcnt lgkmcnt(0)
	v_cvt_pk_bf16_f32 v14, v22, v23
	ds_read2_b32 v[16:17], v9 offset0:82 offset1:115
	s_waitcnt lgkmcnt(0)
	v_cvt_pk_bf16_f32 v15, v16, v17
	ds_read2_b32 v[16:17], v9 offset0:148 offset1:181
	s_waitcnt lgkmcnt(0)
	v_cvt_pk_bf16_f32 v16, v16, v17
	ds_read2_b32 v[22:23], v9 offset0:214 offset1:247
	s_waitcnt lgkmcnt(0)
	v_cvt_pk_bf16_f32 v17, v22, v23
	ds_read2_b32 v[22:23], v9 offset0:24 offset1:57
	global_store_dwordx4 v[26:27], v[14:17], off nt
	v_cmp_lt_i32_e32 vcc, s59, v13
	s_or_b64 s[6:7], vcc, s[6:7]
	s_waitcnt lgkmcnt(0)
	v_cvt_pk_bf16_f32 v14, v22, v23
	ds_read2_b32 v[16:17], v9 offset0:90 offset1:123
	s_waitcnt lgkmcnt(0)
	v_cvt_pk_bf16_f32 v15, v16, v17
	ds_read2_b32 v[16:17], v9 offset0:156 offset1:189
	s_waitcnt lgkmcnt(0)
	v_cvt_pk_bf16_f32 v16, v16, v17
	ds_read2_b32 v[22:23], v9 offset0:222 offset1:255
	s_waitcnt lgkmcnt(0)
	v_cvt_pk_bf16_f32 v17, v22, v23
	global_store_dwordx4 v[18:19], v[14:17], off nt
	s_waitcnt lgkmcnt(0)
	s_andn2_b64 exec, exec, s[6:7]
	s_cbranch_execnz .LBB0_113

.LBB0_116:
	v_mul_hi_i32 v12, v24, s11
	v_lshrrev_b32_e32 v13, 31, v12
	v_ashrrev_i32_e32 v12, 5, v12
	v_add_u32_e32 v14, v12, v13
	v_mad_u64_u32 v[12:13], s[60:61], v14, s12, v[10:11]
	v_and_b32_e32 v13, 0xe0, v12
	v_bfe_u32 v25, v12, 6, 2
	v_lshlrev_b32_e32 v14, 6, v14
	v_subrev_u32_e32 v32, 64, v13
	v_cmp_eq_u32_e32 vcc, 2, v25
	v_or_b32_e32 v26, v14, v47
	v_ashrrev_i32_e32 v15, 31, v14
	v_add_u32_e32 v31, 64, v13
	v_cndmask_b32_e32 v13, v13, v32, vcc
	v_cmp_eq_u32_e32 vcc, 1, v25
	v_and_b32_e32 v30, 0xffffff00, v12
	v_ashrrev_i32_e32 v27, 31, v26
	v_lshl_add_u64 v[28:29], v[14:15], 2, v[6:7]
	v_cndmask_b32_e32 v13, v13, v31, vcc
	v_lshlrev_b64 v[26:27], 15, v[26:27]
	global_load_dword v51, v[28:29], off
	global_load_dword v96, v[28:29], off offset:8
	global_load_dword v97, v[28:29], off offset:16
	global_load_dword v98, v[28:29], off offset:24
	global_load_dword v99, v[28:29], off offset:32
	global_load_dword v100, v[28:29], off offset:40
	global_load_dword v101, v[28:29], off offset:48
	global_load_dword v102, v[28:29], off offset:56
	global_load_dword v103, v[28:29], off offset:64
	global_load_dword v104, v[28:29], off offset:72
	global_load_dword v105, v[28:29], off offset:80
	global_load_dword v106, v[28:29], off offset:88
	global_load_dword v107, v[28:29], off offset:96
	global_load_dword v108, v[28:29], off offset:104
	global_load_dword v109, v[28:29], off offset:112
	global_load_dword v110, v[28:29], off offset:120
	global_load_dword v111, v[28:29], off offset:128
	global_load_dword v112, v[28:29], off offset:136
	global_load_dword v113, v[28:29], off offset:144
	global_load_dword v114, v[28:29], off offset:152
	global_load_dword v115, v[28:29], off offset:160
	global_load_dword v116, v[28:29], off offset:168
	global_load_dword v117, v[28:29], off offset:176
	global_load_dword v118, v[28:29], off offset:184
	global_load_dword v119, v[28:29], off offset:192
	global_load_dword v120, v[28:29], off offset:200
	global_load_dword v121, v[28:29], off offset:208
	global_load_dword v122, v[28:29], off offset:216
	global_load_dword v123, v[28:29], off offset:224
	global_load_dword v124, v[28:29], off offset:232
	global_load_dword v125, v[28:29], off offset:240
	global_load_dword v126, v[28:29], off offset:248
	v_add_u32_e32 v28, v13, v30
	v_lshl_add_u64 v[26:27], s[0:1], 0, v[26:27]
	v_ashrrev_i32_e32 v29, 31, v28
	v_lshl_add_u64 v[26:27], v[28:29], 2, v[26:27]
	v_lshl_add_u64 v[26:27], v[26:27], 0, v[4:5]
	v_add_co_u32_e32 v28, vcc, s13, v26
	v_add_u32_e32 v24, s24, v24
	s_nop 0
	v_addc_co_u32_e32 v29, vcc, 0, v27, vcc
	v_add_co_u32_e32 v30, vcc, s22, v26
	v_add_u32_e32 v10, s10, v10
	s_nop 0
	v_addc_co_u32_e32 v31, vcc, 0, v27, vcc
	v_add_co_u32_e32 v32, vcc, s23, v26
	s_nop 1
	v_addc_co_u32_e32 v33, vcc, 0, v27, vcc
	v_add_co_u32_e32 v34, vcc, s25, v26
	s_nop 1
	v_addc_co_u32_e32 v35, vcc, 0, v27, vcc
	v_add_co_u32_e32 v36, vcc, s26, v26
	s_nop 1
	v_addc_co_u32_e32 v37, vcc, 0, v27, vcc
	v_add_co_u32_e32 v38, vcc, s27, v26
	s_nop 1
	v_addc_co_u32_e32 v39, vcc, 0, v27, vcc
	v_add_co_u32_e32 v40, vcc, s28, v26
	s_nop 1
	v_addc_co_u32_e32 v41, vcc, 0, v27, vcc
	v_add_co_u32_e32 v42, vcc, s29, v26
	s_nop 1
	v_addc_co_u32_e32 v43, vcc, 0, v27, vcc
	v_add_co_u32_e32 v44, vcc, s30, v26
	s_nop 1
	v_addc_co_u32_e32 v45, vcc, 0, v27, vcc
	v_add_co_u32_e32 v52, vcc, s31, v26
	s_nop 1
	v_addc_co_u32_e32 v53, vcc, 0, v27, vcc
	v_add_co_u32_e32 v54, vcc, s34, v26
	s_nop 1
	v_addc_co_u32_e32 v55, vcc, 0, v27, vcc
	v_add_co_u32_e32 v56, vcc, s35, v26
	s_nop 1
	v_addc_co_u32_e32 v57, vcc, 0, v27, vcc
	v_add_co_u32_e32 v58, vcc, s36, v26
	s_nop 1
	v_addc_co_u32_e32 v59, vcc, 0, v27, vcc
	v_add_co_u32_e32 v60, vcc, s37, v26
	s_nop 1
	v_addc_co_u32_e32 v61, vcc, 0, v27, vcc
	v_add_co_u32_e32 v62, vcc, s38, v26
	s_nop 1
	v_addc_co_u32_e32 v63, vcc, 0, v27, vcc
	v_add_co_u32_e32 v64, vcc, s39, v26
	s_nop 1
	v_addc_co_u32_e32 v65, vcc, 0, v27, vcc
	v_add_co_u32_e32 v66, vcc, s40, v26
	s_nop 1
	v_addc_co_u32_e32 v67, vcc, 0, v27, vcc
	v_add_co_u32_e32 v68, vcc, s41, v26
	s_nop 1
	v_addc_co_u32_e32 v69, vcc, 0, v27, vcc
	v_add_co_u32_e32 v70, vcc, s42, v26
	s_nop 1
	v_addc_co_u32_e32 v71, vcc, 0, v27, vcc
	v_add_co_u32_e32 v72, vcc, s43, v26
	s_nop 1
	v_addc_co_u32_e32 v73, vcc, 0, v27, vcc
	v_add_co_u32_e32 v74, vcc, s46, v26
	s_nop 1
	v_addc_co_u32_e32 v75, vcc, 0, v27, vcc
	v_add_co_u32_e32 v76, vcc, s47, v26
	s_nop 1
	v_addc_co_u32_e32 v77, vcc, 0, v27, vcc
	v_add_co_u32_e32 v78, vcc, s48, v26
	s_nop 1
	v_addc_co_u32_e32 v79, vcc, 0, v27, vcc
	v_add_co_u32_e32 v80, vcc, s49, v26
	s_nop 1
	v_addc_co_u32_e32 v81, vcc, 0, v27, vcc
	v_add_co_u32_e32 v82, vcc, s50, v26
	s_nop 1
	v_addc_co_u32_e32 v83, vcc, 0, v27, vcc
	v_add_co_u32_e32 v84, vcc, s51, v26
	s_nop 1
	v_addc_co_u32_e32 v85, vcc, 0, v27, vcc
	v_add_co_u32_e32 v86, vcc, s54, v26
	s_nop 1
	v_addc_co_u32_e32 v87, vcc, 0, v27, vcc
	v_add_co_u32_e32 v88, vcc, s55, v26
	s_nop 1
	v_addc_co_u32_e32 v89, vcc, 0, v27, vcc
	v_add_co_u32_e32 v90, vcc, s56, v26
	s_nop 1
	v_addc_co_u32_e32 v91, vcc, 0, v27, vcc
	v_add_co_u32_e32 v92, vcc, s57, v26
	s_nop 1
	v_addc_co_u32_e32 v93, vcc, 0, v27, vcc
	v_add_co_u32_e32 v94, vcc, s58, v26
	s_nop 1
	v_addc_co_u32_e32 v95, vcc, 0, v27, vcc
	global_load_dword v25, v[26:27], off nt
	global_load_dword v127, v[28:29], off nt
	global_load_dword v128, v[30:31], off nt
	global_load_dword v129, v[32:33], off nt
	global_load_dword v130, v[34:35], off nt
	s_nop 0
	global_load_dword v36, v[36:37], off nt
	s_nop 0
	global_load_dword v37, v[38:39], off nt
	s_nop 0
	global_load_dword v38, v[40:41], off nt
	global_load_dword v39, v[42:43], off nt
	s_nop 0
	global_load_dword v40, v[44:45], off nt
	global_load_dword v41, v[52:53], off nt
	global_load_dword v42, v[54:55], off nt
	global_load_dword v43, v[56:57], off nt
	s_nop 0
	global_load_dword v44, v[58:59], off nt
	global_load_dword v45, v[60:61], off nt
	global_load_dword v52, v[62:63], off nt
	global_load_dword v53, v[64:65], off nt
	global_load_dword v54, v[66:67], off nt
	global_load_dword v55, v[68:69], off nt
	global_load_dword v56, v[70:71], off nt
	global_load_dword v57, v[72:73], off nt
	global_load_dword v58, v[74:75], off nt
	global_load_dword v59, v[76:77], off nt
	global_load_dword v60, v[78:79], off nt
	global_load_dword v61, v[80:81], off nt
	global_load_dword v62, v[82:83], off nt
	global_load_dword v63, v[84:85], off nt
	global_load_dword v64, v[86:87], off nt
	global_load_dword v65, v[88:89], off nt
	global_load_dword v66, v[90:91], off nt
	global_load_dword v67, v[92:93], off nt
	global_load_dword v68, v[94:95], off nt
	v_add_u32_e32 v26, v12, v48
	v_add_u32_e32 v12, 8, v26
	v_lshl_add_u64 v[28:29], v[14:15], 1, v[8:9]
	v_add_u32_e32 v14, 16, v26
	v_ashrrev_i32_e32 v13, 31, v12
	v_ashrrev_i32_e32 v15, 31, v14
	v_lshlrev_b64 v[12:13], 12, v[12:13]
	v_ashrrev_i32_e32 v27, 31, v26
	v_lshlrev_b64 v[14:15], 12, v[14:15]
	v_lshl_add_u64 v[32:33], v[28:29], 0, v[12:13]
	v_lshlrev_b64 v[30:31], 12, v[26:27]
	v_lshl_add_u64 v[34:35], v[28:29], 0, v[14:15]
	v_lshl_add_u64 v[30:31], v[28:29], 0, v[30:31]
	v_add_u32_e32 v26, 24, v26
	v_cmp_lt_i32_e32 vcc, s59, v24
	s_or_b64 s[4:5], vcc, s[4:5]
	s_waitcnt vmcnt(31)
	v_mul_f32_e32 v12, v25, v51
	s_waitcnt vmcnt(30)
	v_mul_f32_e32 v13, v127, v96
	s_waitcnt vmcnt(29)
	v_mul_f32_e32 v14, v128, v97
	s_waitcnt vmcnt(28)
	v_mul_f32_e32 v15, v129, v98
	s_waitcnt vmcnt(27)
	v_mul_f32_e32 v25, v130, v99
	s_waitcnt vmcnt(26)
	v_mul_f32_e32 v27, v36, v100
	s_waitcnt vmcnt(25)
	v_mul_f32_e32 v36, v37, v101
	s_waitcnt vmcnt(24)
	v_mul_f32_e32 v37, v38, v102
	s_waitcnt vmcnt(23)
	v_mul_f32_e32 v38, v39, v103
	s_waitcnt vmcnt(22)
	v_mul_f32_e32 v39, v40, v104
	s_waitcnt vmcnt(21)
	v_mul_f32_e32 v40, v41, v105
	s_waitcnt vmcnt(20)
	v_mul_f32_e32 v41, v42, v106
	s_waitcnt vmcnt(19)
	v_mul_f32_e32 v42, v43, v107
	s_waitcnt vmcnt(18)
	v_mul_f32_e32 v43, v44, v108
	s_waitcnt vmcnt(17)
	v_mul_f32_e32 v44, v45, v109
	s_waitcnt vmcnt(16)
	v_mul_f32_e32 v45, v52, v110
	s_waitcnt vmcnt(15)
	v_mul_f32_e32 v51, v53, v111
	s_waitcnt vmcnt(14)
	v_mul_f32_e32 v52, v54, v112
	s_waitcnt vmcnt(13)
	v_mul_f32_e32 v53, v55, v113
	s_waitcnt vmcnt(12)
	v_mul_f32_e32 v54, v56, v114
	s_waitcnt vmcnt(11)
	v_mul_f32_e32 v55, v57, v115
	s_waitcnt vmcnt(10)
	v_mul_f32_e32 v56, v58, v116
	s_waitcnt vmcnt(9)
	v_mul_f32_e32 v57, v59, v117
	s_waitcnt vmcnt(8)
	v_mul_f32_e32 v58, v60, v118
	s_waitcnt vmcnt(7)
	v_mul_f32_e32 v59, v61, v119
	s_waitcnt vmcnt(6)
	v_mul_f32_e32 v60, v62, v120
	s_waitcnt vmcnt(5)
	v_mul_f32_e32 v61, v63, v121
	s_waitcnt vmcnt(4)
	v_mul_f32_e32 v62, v64, v122
	s_waitcnt vmcnt(3)
	v_mul_f32_e32 v63, v65, v123
	s_waitcnt vmcnt(2)
	v_mul_f32_e32 v64, v66, v124
	s_waitcnt vmcnt(1)
	v_mul_f32_e32 v65, v67, v125
	s_waitcnt vmcnt(0)
	v_mul_f32_e32 v66, v68, v126
	ds_write2_b32 v16, v12, v13 offset1:66
	ds_write2_b32 v16, v14, v15 offset0:132 offset1:198
	ds_write2_b32 v17, v25, v27 offset0:8 offset1:74
	ds_write2_b32 v17, v36, v37 offset0:140 offset1:206
	ds_write2_b32 v18, v38, v39 offset0:16 offset1:82
	ds_write2_b32 v18, v40, v41 offset0:148 offset1:214
	ds_write2_b32 v19, v42, v43 offset0:24 offset1:90
	ds_write2_b32 v19, v44, v45 offset0:156 offset1:222
	ds_write2_b32 v20, v51, v52 offset0:32 offset1:98
	ds_write2_b32 v20, v53, v54 offset0:164 offset1:230
	ds_write2_b32 v21, v55, v56 offset0:40 offset1:106
	ds_write2_b32 v21, v57, v58 offset0:172 offset1:238
	ds_write2_b32 v22, v59, v60 offset0:48 offset1:114
	ds_write2_b32 v22, v61, v62 offset0:180 offset1:246
	ds_write2_b32 v23, v63, v64 offset0:56 offset1:122
	ds_write2_b32 v23, v65, v66 offset0:188 offset1:254
	s_waitcnt lgkmcnt(0)
	ds_read2_b32 v[12:13], v11 offset1:33
	s_waitcnt lgkmcnt(0)
	v_cvt_pk_bf16_f32 v12, v12, v13
	ds_read2_b32 v[14:15], v11 offset0:66 offset1:99
	s_waitcnt lgkmcnt(0)
	v_cvt_pk_bf16_f32 v13, v14, v15
	ds_read2_b32 v[14:15], v11 offset0:132 offset1:165
	s_waitcnt lgkmcnt(0)
	v_cvt_pk_bf16_f32 v14, v14, v15
	ds_read2_b32 v[36:37], v11 offset0:198 offset1:231
	s_waitcnt lgkmcnt(0)
	v_cvt_pk_bf16_f32 v15, v36, v37
	ds_read2_b32 v[36:37], v11 offset0:8 offset1:41
	global_store_dwordx4 v[30:31], v[12:15], off nt
	v_ashrrev_i32_e32 v27, 31, v26
	v_lshlrev_b64 v[26:27], 12, v[26:27]
	s_waitcnt lgkmcnt(0)
	v_cvt_pk_bf16_f32 v12, v36, v37
	ds_read2_b32 v[14:15], v11 offset0:74 offset1:107
	s_waitcnt lgkmcnt(0)
	v_cvt_pk_bf16_f32 v13, v14, v15
	ds_read2_b32 v[14:15], v11 offset0:140 offset1:173
	s_waitcnt lgkmcnt(0)
	v_cvt_pk_bf16_f32 v14, v14, v15
	ds_read2_b32 v[30:31], v11 offset0:206 offset1:239
	s_waitcnt lgkmcnt(0)
	v_cvt_pk_bf16_f32 v15, v30, v31
	ds_read2_b32 v[30:31], v11 offset0:16 offset1:49
	global_store_dwordx4 v[32:33], v[12:15], off nt
	v_lshl_add_u64 v[26:27], v[28:29], 0, v[26:27]
	s_waitcnt lgkmcnt(0)
	v_cvt_pk_bf16_f32 v12, v30, v31
	ds_read2_b32 v[14:15], v11 offset0:82 offset1:115
	s_waitcnt lgkmcnt(0)
	v_cvt_pk_bf16_f32 v13, v14, v15
	ds_read2_b32 v[14:15], v11 offset0:148 offset1:181
	s_waitcnt lgkmcnt(0)
	v_cvt_pk_bf16_f32 v14, v14, v15
	ds_read2_b32 v[30:31], v11 offset0:214 offset1:247
	s_waitcnt lgkmcnt(0)
	v_cvt_pk_bf16_f32 v15, v30, v31
	ds_read2_b32 v[30:31], v11 offset0:24 offset1:57
	global_store_dwordx4 v[34:35], v[12:15], off nt
	s_waitcnt lgkmcnt(0)
	s_nop 0
	v_cvt_pk_bf16_f32 v12, v30, v31
	ds_read2_b32 v[14:15], v11 offset0:90 offset1:123
	s_waitcnt lgkmcnt(0)
	v_cvt_pk_bf16_f32 v13, v14, v15
	ds_read2_b32 v[14:15], v11 offset0:156 offset1:189
	s_waitcnt lgkmcnt(0)
	v_cvt_pk_bf16_f32 v14, v14, v15
	ds_read2_b32 v[30:31], v11 offset0:222 offset1:255
	s_waitcnt lgkmcnt(0)
	v_cvt_pk_bf16_f32 v15, v30, v31
	global_store_dwordx4 v[26:27], v[12:15], off nt
	s_waitcnt lgkmcnt(0)
	s_andn2_b64 exec, exec, s[4:5]
	s_cbranch_execnz .LBB0_116

.LBB0_119:
	v_ashrrev_i32_e32 v2, 31, v21
	v_lshrrev_b32_e32 v2, 26, v2
	v_add_u32_e32 v2, v21, v2
	v_lshlrev_b32_e32 v3, 5, v2
	v_and_b32_e32 v2, 0xffffffc0, v2
	v_and_b32_e32 v23, 0xfffff800, v3
	v_or_b32_e32 v22, v2, v47
	v_sub_u32_e32 v24, v20, v23
	v_ashrrev_i32_e32 v23, 31, v22
	v_lshlrev_b64 v[22:23], 15, v[22:23]
	v_ashrrev_i32_e32 v25, 31, v24
	v_lshl_add_u64 v[22:23], s[0:1], 0, v[22:23]
	v_ashrrev_i32_e32 v3, 31, v2
	v_lshl_add_u64 v[22:23], v[24:25], 2, v[22:23]
	v_lshl_add_u64 v[26:27], v[2:3], 2, v[8:9]
	v_lshl_add_u64 v[22:23], v[22:23], 0, v[4:5]
	global_load_dword v92, v[26:27], off
	global_load_dword v93, v[26:27], off offset:8
	global_load_dword v94, v[26:27], off offset:16
	global_load_dword v95, v[26:27], off offset:24
	global_load_dword v96, v[26:27], off offset:32
	global_load_dword v97, v[26:27], off offset:40
	global_load_dword v98, v[26:27], off offset:48
	global_load_dword v99, v[26:27], off offset:56
	global_load_dword v100, v[26:27], off offset:64
	global_load_dword v101, v[26:27], off offset:72
	global_load_dword v102, v[26:27], off offset:80
	global_load_dword v103, v[26:27], off offset:88
	global_load_dword v104, v[26:27], off offset:96
	global_load_dword v105, v[26:27], off offset:104
	global_load_dword v106, v[26:27], off offset:112
	global_load_dword v107, v[26:27], off offset:120
	global_load_dword v108, v[26:27], off offset:128
	global_load_dword v109, v[26:27], off offset:136
	global_load_dword v110, v[26:27], off offset:144
	global_load_dword v111, v[26:27], off offset:152
	global_load_dword v112, v[26:27], off offset:160
	global_load_dword v113, v[26:27], off offset:168
	global_load_dword v114, v[26:27], off offset:176
	global_load_dword v115, v[26:27], off offset:184
	global_load_dword v116, v[26:27], off offset:192
	global_load_dword v117, v[26:27], off offset:200
	global_load_dword v118, v[26:27], off offset:208
	global_load_dword v119, v[26:27], off offset:216
	global_load_dword v120, v[26:27], off offset:224
	global_load_dword v121, v[26:27], off offset:232
	global_load_dword v122, v[26:27], off offset:240
	global_load_dword v123, v[26:27], off offset:248
	v_add_co_u32_e32 v26, vcc, s7, v22
	v_lshl_add_u64 v[2:3], v[2:3], 1, v[10:11]
	s_nop 0
	v_addc_co_u32_e32 v27, vcc, 0, v23, vcc
	v_add_co_u32_e32 v28, vcc, s8, v22
	v_add_u32_e32 v21, s24, v21
	s_nop 0
	v_addc_co_u32_e32 v29, vcc, 0, v23, vcc
	v_add_co_u32_e32 v30, vcc, s9, v22
	v_add_u32_e32 v20, s6, v20
	s_nop 0
	v_addc_co_u32_e32 v31, vcc, 0, v23, vcc
	v_add_co_u32_e32 v32, vcc, s10, v22
	s_nop 1
	v_addc_co_u32_e32 v33, vcc, 0, v23, vcc
	v_add_co_u32_e32 v34, vcc, s11, v22
	s_nop 1
	v_addc_co_u32_e32 v35, vcc, 0, v23, vcc
	v_add_co_u32_e32 v36, vcc, s12, v22
	s_nop 1
	v_addc_co_u32_e32 v37, vcc, 0, v23, vcc
	v_add_co_u32_e32 v38, vcc, s13, v22
	s_nop 1
	v_addc_co_u32_e32 v39, vcc, 0, v23, vcc
	v_add_co_u32_e32 v40, vcc, s22, v22
	s_nop 1
	v_addc_co_u32_e32 v41, vcc, 0, v23, vcc
	v_add_co_u32_e32 v42, vcc, s23, v22
	s_nop 1
	v_addc_co_u32_e32 v43, vcc, 0, v23, vcc
	v_add_co_u32_e32 v44, vcc, s25, v22
	s_nop 1
	v_addc_co_u32_e32 v45, vcc, 0, v23, vcc
	v_add_co_u32_e32 v50, vcc, s26, v22
	s_nop 1
	v_addc_co_u32_e32 v51, vcc, 0, v23, vcc
	v_add_co_u32_e32 v52, vcc, s27, v22
	s_nop 1
	v_addc_co_u32_e32 v53, vcc, 0, v23, vcc
	v_add_co_u32_e32 v54, vcc, s28, v22
	s_nop 1
	v_addc_co_u32_e32 v55, vcc, 0, v23, vcc
	v_add_co_u32_e32 v56, vcc, s29, v22
	s_nop 1
	v_addc_co_u32_e32 v57, vcc, 0, v23, vcc
	v_add_co_u32_e32 v58, vcc, s30, v22
	s_nop 1
	v_addc_co_u32_e32 v59, vcc, 0, v23, vcc
	v_add_co_u32_e32 v60, vcc, s31, v22
	s_nop 1
	v_addc_co_u32_e32 v61, vcc, 0, v23, vcc
	v_add_co_u32_e32 v62, vcc, s34, v22
	s_nop 1
	v_addc_co_u32_e32 v63, vcc, 0, v23, vcc
	v_add_co_u32_e32 v64, vcc, s35, v22
	s_nop 1
	v_addc_co_u32_e32 v65, vcc, 0, v23, vcc
	v_add_co_u32_e32 v66, vcc, s36, v22
	s_nop 1
	v_addc_co_u32_e32 v67, vcc, 0, v23, vcc
	v_add_co_u32_e32 v68, vcc, s37, v22
	s_nop 1
	v_addc_co_u32_e32 v69, vcc, 0, v23, vcc
	v_add_co_u32_e32 v70, vcc, s38, v22
	s_nop 1
	v_addc_co_u32_e32 v71, vcc, 0, v23, vcc
	v_add_co_u32_e32 v72, vcc, s39, v22
	s_nop 1
	v_addc_co_u32_e32 v73, vcc, 0, v23, vcc
	v_add_co_u32_e32 v74, vcc, s40, v22
	s_nop 1
	v_addc_co_u32_e32 v75, vcc, 0, v23, vcc
	v_add_co_u32_e32 v76, vcc, s41, v22
	s_nop 1
	v_addc_co_u32_e32 v77, vcc, 0, v23, vcc
	v_add_co_u32_e32 v78, vcc, s42, v22
	s_nop 1
	v_addc_co_u32_e32 v79, vcc, 0, v23, vcc
	v_add_co_u32_e32 v80, vcc, s43, v22
	s_nop 1
	v_addc_co_u32_e32 v81, vcc, 0, v23, vcc
	v_add_co_u32_e32 v82, vcc, s46, v22
	s_nop 1
	v_addc_co_u32_e32 v83, vcc, 0, v23, vcc
	v_add_co_u32_e32 v84, vcc, s47, v22
	s_nop 1
	v_addc_co_u32_e32 v85, vcc, 0, v23, vcc
	v_add_co_u32_e32 v86, vcc, s48, v22
	s_nop 1
	v_addc_co_u32_e32 v87, vcc, 0, v23, vcc
	v_add_co_u32_e32 v88, vcc, s49, v22
	s_nop 1
	v_addc_co_u32_e32 v89, vcc, 0, v23, vcc
	v_add_co_u32_e32 v90, vcc, s50, v22
	s_nop 1
	v_addc_co_u32_e32 v91, vcc, 0, v23, vcc
	v_add_co_u32_e32 v22, vcc, s51, v22
	s_nop 1
	v_addc_co_u32_e32 v23, vcc, 0, v23, vcc
	global_load_dword v124, v[26:27], off nt
	global_load_dword v125, v[28:29], off nt
	global_load_dword v126, v[30:31], off nt
	global_load_dword v127, v[32:33], off nt
	s_nop 0
	global_load_dword v34, v[34:35], off nt
	s_nop 0
	global_load_dword v35, v[36:37], off nt
	s_nop 0
	global_load_dword v36, v[38:39], off nt
	global_load_dword v37, v[40:41], off nt
	s_nop 0
	global_load_dword v38, v[42:43], off nt
	global_load_dword v39, v[44:45], off nt
	global_load_dword v40, v[50:51], off nt
	global_load_dword v41, v[52:53], off nt
	s_nop 0
	global_load_dword v42, v[54:55], off nt
	global_load_dword v43, v[56:57], off nt
	global_load_dword v44, v[58:59], off nt
	global_load_dword v45, v[60:61], off nt
	global_load_dword v50, v[62:63], off nt
	global_load_dword v51, v[64:65], off nt
	global_load_dword v52, v[66:67], off nt
	global_load_dword v53, v[68:69], off nt
	global_load_dword v54, v[70:71], off nt
	global_load_dword v55, v[72:73], off nt
	global_load_dword v56, v[74:75], off nt
	global_load_dword v57, v[76:77], off nt
	global_load_dword v58, v[78:79], off nt
	global_load_dword v59, v[80:81], off nt
	global_load_dword v60, v[82:83], off nt
	global_load_dword v61, v[84:85], off nt
	global_load_dword v62, v[86:87], off nt
	global_load_dword v63, v[88:89], off nt
	global_load_dword v64, v[90:91], off nt
	global_load_dword v65, v[22:23], off nt
	v_add_u32_e32 v26, v24, v48
	v_add_u32_e32 v22, 8, v26
	v_add_u32_e32 v24, 16, v26
	v_ashrrev_i32_e32 v23, 31, v22
	v_ashrrev_i32_e32 v25, 31, v24
	v_lshlrev_b64 v[22:23], 12, v[22:23]
	v_ashrrev_i32_e32 v27, 31, v26
	v_lshlrev_b64 v[24:25], 12, v[24:25]
	v_lshl_add_u64 v[30:31], v[2:3], 0, v[22:23]
	v_lshlrev_b64 v[28:29], 12, v[26:27]
	v_lshl_add_u64 v[32:33], v[2:3], 0, v[24:25]
	v_lshl_add_u64 v[28:29], v[2:3], 0, v[28:29]
	v_add_u32_e32 v26, 24, v26
	v_cmp_lt_i32_e32 vcc, s54, v21
	s_or_b64 s[2:3], vcc, s[2:3]
	s_waitcnt vmcnt(31)
	v_mul_f32_e32 v22, v124, v92
	s_waitcnt vmcnt(30)
	v_mul_f32_e32 v23, v125, v93
	s_waitcnt vmcnt(29)
	v_mul_f32_e32 v24, v126, v94
	s_waitcnt vmcnt(28)
	v_mul_f32_e32 v25, v127, v95
	s_waitcnt vmcnt(27)
	v_mul_f32_e32 v27, v34, v96
	s_waitcnt vmcnt(26)
	v_mul_f32_e32 v34, v35, v97
	s_waitcnt vmcnt(25)
	v_mul_f32_e32 v35, v36, v98
	s_waitcnt vmcnt(24)
	v_mul_f32_e32 v36, v37, v99
	s_waitcnt vmcnt(23)
	v_mul_f32_e32 v37, v38, v100
	s_waitcnt vmcnt(22)
	v_mul_f32_e32 v38, v39, v101
	s_waitcnt vmcnt(21)
	v_mul_f32_e32 v39, v40, v102
	s_waitcnt vmcnt(20)
	v_mul_f32_e32 v40, v41, v103
	s_waitcnt vmcnt(19)
	v_mul_f32_e32 v41, v42, v104
	s_waitcnt vmcnt(18)
	v_mul_f32_e32 v42, v43, v105
	s_waitcnt vmcnt(17)
	v_mul_f32_e32 v43, v44, v106
	s_waitcnt vmcnt(16)
	v_mul_f32_e32 v44, v45, v107
	s_waitcnt vmcnt(15)
	v_mul_f32_e32 v45, v50, v108
	s_waitcnt vmcnt(14)
	v_mul_f32_e32 v50, v51, v109
	s_waitcnt vmcnt(13)
	v_mul_f32_e32 v51, v52, v110
	s_waitcnt vmcnt(12)
	v_mul_f32_e32 v52, v53, v111
	s_waitcnt vmcnt(11)
	v_mul_f32_e32 v53, v54, v112
	s_waitcnt vmcnt(10)
	v_mul_f32_e32 v54, v55, v113
	s_waitcnt vmcnt(9)
	v_mul_f32_e32 v55, v56, v114
	s_waitcnt vmcnt(8)
	v_mul_f32_e32 v56, v57, v115
	s_waitcnt vmcnt(7)
	v_mul_f32_e32 v57, v58, v116
	s_waitcnt vmcnt(6)
	v_mul_f32_e32 v58, v59, v117
	s_waitcnt vmcnt(5)
	v_mul_f32_e32 v59, v60, v118
	s_waitcnt vmcnt(4)
	v_mul_f32_e32 v60, v61, v119
	s_waitcnt vmcnt(3)
	v_mul_f32_e32 v61, v62, v120
	s_waitcnt vmcnt(2)
	v_mul_f32_e32 v62, v63, v121
	s_waitcnt vmcnt(1)
	v_mul_f32_e32 v63, v64, v122
	s_waitcnt vmcnt(0)
	v_mul_f32_e32 v64, v65, v123
	ds_write2_b32 v12, v22, v23 offset1:66
	ds_write2_b32 v12, v24, v25 offset0:132 offset1:198
	ds_write2_b32 v13, v27, v34 offset0:8 offset1:74
	ds_write2_b32 v13, v35, v36 offset0:140 offset1:206
	ds_write2_b32 v14, v37, v38 offset0:16 offset1:82
	ds_write2_b32 v14, v39, v40 offset0:148 offset1:214
	ds_write2_b32 v15, v41, v42 offset0:24 offset1:90
	ds_write2_b32 v15, v43, v44 offset0:156 offset1:222
	ds_write2_b32 v16, v45, v50 offset0:32 offset1:98
	ds_write2_b32 v16, v51, v52 offset0:164 offset1:230
	ds_write2_b32 v17, v53, v54 offset0:40 offset1:106
	ds_write2_b32 v17, v55, v56 offset0:172 offset1:238
	ds_write2_b32 v18, v57, v58 offset0:48 offset1:114
	ds_write2_b32 v18, v59, v60 offset0:180 offset1:246
	ds_write2_b32 v19, v61, v62 offset0:56 offset1:122
	ds_write2_b32 v19, v63, v64 offset0:188 offset1:254
	s_waitcnt lgkmcnt(0)
	ds_read2_b32 v[22:23], v7 offset1:33
	s_waitcnt lgkmcnt(0)
	v_cvt_pk_bf16_f32 v22, v22, v23
	ds_read2_b32 v[24:25], v7 offset0:66 offset1:99
	s_waitcnt lgkmcnt(0)
	v_cvt_pk_bf16_f32 v23, v24, v25
	ds_read2_b32 v[24:25], v7 offset0:132 offset1:165
	s_waitcnt lgkmcnt(0)
	v_cvt_pk_bf16_f32 v24, v24, v25
	ds_read2_b32 v[34:35], v7 offset0:198 offset1:231
	s_waitcnt lgkmcnt(0)
	v_cvt_pk_bf16_f32 v25, v34, v35
	ds_read2_b32 v[34:35], v7 offset0:8 offset1:41
	global_store_dwordx4 v[28:29], v[22:25], off nt
	v_ashrrev_i32_e32 v27, 31, v26
	v_lshlrev_b64 v[26:27], 12, v[26:27]
	s_waitcnt lgkmcnt(0)
	v_cvt_pk_bf16_f32 v22, v34, v35
	ds_read2_b32 v[24:25], v7 offset0:74 offset1:107
	s_waitcnt lgkmcnt(0)
	v_cvt_pk_bf16_f32 v23, v24, v25
	ds_read2_b32 v[24:25], v7 offset0:140 offset1:173
	s_waitcnt lgkmcnt(0)
	v_cvt_pk_bf16_f32 v24, v24, v25
	ds_read2_b32 v[28:29], v7 offset0:206 offset1:239
	s_waitcnt lgkmcnt(0)
	v_cvt_pk_bf16_f32 v25, v28, v29
	ds_read2_b32 v[28:29], v7 offset0:16 offset1:49
	global_store_dwordx4 v[30:31], v[22:25], off nt
	v_lshl_add_u64 v[2:3], v[2:3], 0, v[26:27]
	s_waitcnt lgkmcnt(0)
	v_cvt_pk_bf16_f32 v22, v28, v29
	ds_read2_b32 v[24:25], v7 offset0:82 offset1:115
	s_waitcnt lgkmcnt(0)
	v_cvt_pk_bf16_f32 v23, v24, v25
	ds_read2_b32 v[24:25], v7 offset0:148 offset1:181
	s_waitcnt lgkmcnt(0)
	v_cvt_pk_bf16_f32 v24, v24, v25
	ds_read2_b32 v[28:29], v7 offset0:214 offset1:247
	s_waitcnt lgkmcnt(0)
	v_cvt_pk_bf16_f32 v25, v28, v29
	ds_read2_b32 v[28:29], v7 offset0:24 offset1:57
	global_store_dwordx4 v[32:33], v[22:25], off nt
	s_waitcnt lgkmcnt(0)
	s_nop 0
	v_cvt_pk_bf16_f32 v22, v28, v29
	ds_read2_b32 v[24:25], v7 offset0:90 offset1:123
	s_waitcnt lgkmcnt(0)
	v_cvt_pk_bf16_f32 v23, v24, v25
	ds_read2_b32 v[24:25], v7 offset0:156 offset1:189
	s_waitcnt lgkmcnt(0)
	v_cvt_pk_bf16_f32 v24, v24, v25
	ds_read2_b32 v[28:29], v7 offset0:222 offset1:255
	s_waitcnt lgkmcnt(0)
	v_cvt_pk_bf16_f32 v25, v28, v29
	global_store_dwordx4 v[2:3], v[22:25], off nt
	s_waitcnt lgkmcnt(0)
	s_andn2_b64 exec, exec, s[2:3]
	s_cbranch_execnz .LBB0_119
	s_or_b64 exec, exec, s[2:3]
	v_mov_b32_e32 v5, 0
	v_lshlrev_b32_e32 v2, 1, v6
	v_mov_b32_e32 v3, v5
	s_add_u32 s0, s14, 0x1000000
	v_lshl_add_u64 v[2:3], s[94:95], 0, v[2:3]
	s_mov_b64 s[2:3], 0x6000000
	s_addc_u32 s1, s15, 0
	v_lshl_add_u64 v[2:3], v[2:3], 0, s[2:3]
	s_mov_b64 s[2:3], 0
	s_movk_i32 s7, 0x4000
	s_mov_b32 s8, 0x8000
	s_mov_b32 s9, 0xc000
	s_mov_b32 s10, 0x10000
	s_mov_b32 s11, 0x14000
	s_mov_b32 s12, 0x18000
	s_mov_b32 s13, 0x1c000
	s_mov_b32 s14, 0x20000
	s_mov_b32 s15, 0x24000
	s_mov_b32 s22, 0x28000
	s_mov_b32 s23, 0x2c000
	s_mov_b32 s25, 0x30000
	s_mov_b32 s26, 0x34000
	s_mov_b32 s27, 0x38000
	s_mov_b32 s28, 0x3c000
	s_mov_b32 s29, 0x40000
	s_mov_b32 s30, 0x44000
	s_mov_b32 s31, 0x48000
	s_mov_b32 s34, 0x4c000
	s_mov_b32 s35, 0x50000
	s_mov_b32 s36, 0x54000
	s_mov_b32 s37, 0x58000
	s_mov_b32 s38, 0x5c000
	s_mov_b32 s39, 0x60000
	s_mov_b32 s40, 0x64000
	s_mov_b32 s41, 0x68000
	s_mov_b32 s42, 0x6c000
	s_mov_b32 s43, 0x70000
	s_mov_b32 s46, 0x74000
	s_mov_b32 s47, 0x78000
	s_mov_b32 s48, 0x7c000
	s_movk_i32 s49, 0x7ff
.LBB0_121:
	v_ashrrev_i32_e32 v6, 31, v46
	v_lshrrev_b32_e32 v6, 26, v6
	v_add_u32_e32 v6, v46, v6
	v_and_b32_e32 v8, 0xffffffc0, v6
	v_lshlrev_b32_e32 v9, 5, v6
	v_or_b32_e32 v10, v8, v47
	v_and_b32_e32 v6, 0xfffff800, v9
	v_ashrrev_i32_e32 v11, 31, v10
	v_sub_u32_e32 v14, v49, v6
	v_lshlrev_b64 v[10:11], 13, v[10:11]
	v_ashrrev_i32_e32 v15, 31, v14
	v_lshl_add_u64 v[10:11], s[0:1], 0, v[10:11]
	v_lshl_add_u64 v[10:11], v[14:15], 2, v[10:11]
	v_lshl_add_u64 v[10:11], v[10:11], 0, v[4:5]
	v_add_co_u32_e32 v16, vcc, s7, v10
	v_ashrrev_i32_e32 v9, 31, v8
	s_nop 0
	v_addc_co_u32_e32 v17, vcc, 0, v11, vcc
	v_add_co_u32_e32 v18, vcc, s8, v10
	v_add_u32_e32 v14, v14, v48
	s_nop 0
	v_addc_co_u32_e32 v19, vcc, 0, v11, vcc
	v_add_co_u32_e32 v20, vcc, s9, v10
	v_ashrrev_i32_e32 v15, 31, v14
	s_nop 0
	v_addc_co_u32_e32 v21, vcc, 0, v11, vcc
	v_add_co_u32_e32 v22, vcc, s10, v10
	v_add_u32_e32 v46, s24, v46
	s_nop 0
	v_addc_co_u32_e32 v23, vcc, 0, v11, vcc
	v_add_co_u32_e32 v24, vcc, s11, v10
	v_add_u32_e32 v49, s6, v49
	s_nop 0
	v_addc_co_u32_e32 v25, vcc, 0, v11, vcc
	v_add_co_u32_e32 v26, vcc, s12, v10
	s_nop 1
	v_addc_co_u32_e32 v27, vcc, 0, v11, vcc
	v_add_co_u32_e32 v28, vcc, s13, v10
	s_nop 1
	v_addc_co_u32_e32 v29, vcc, 0, v11, vcc
	v_add_co_u32_e32 v30, vcc, s14, v10
	s_nop 1
	v_addc_co_u32_e32 v31, vcc, 0, v11, vcc
	v_add_co_u32_e32 v32, vcc, s15, v10
	s_nop 1
	v_addc_co_u32_e32 v33, vcc, 0, v11, vcc
	v_add_co_u32_e32 v34, vcc, s22, v10
	s_nop 1
	v_addc_co_u32_e32 v35, vcc, 0, v11, vcc
	v_add_co_u32_e32 v36, vcc, s23, v10
	s_nop 1
	v_addc_co_u32_e32 v37, vcc, 0, v11, vcc
	v_add_co_u32_e32 v38, vcc, s25, v10
	s_nop 1
	v_addc_co_u32_e32 v39, vcc, 0, v11, vcc
	v_add_co_u32_e32 v40, vcc, s26, v10
	s_nop 1
	v_addc_co_u32_e32 v41, vcc, 0, v11, vcc
	v_add_co_u32_e32 v42, vcc, s27, v10
	s_nop 1
	v_addc_co_u32_e32 v43, vcc, 0, v11, vcc
	v_add_co_u32_e32 v44, vcc, s28, v10
	s_nop 1
	v_addc_co_u32_e32 v45, vcc, 0, v11, vcc
	v_add_co_u32_e32 v50, vcc, s29, v10
	s_nop 1
	v_addc_co_u32_e32 v51, vcc, 0, v11, vcc
	v_add_co_u32_e32 v52, vcc, s30, v10
	s_nop 1
	v_addc_co_u32_e32 v53, vcc, 0, v11, vcc
	v_add_co_u32_e32 v54, vcc, s31, v10
	s_nop 1
	v_addc_co_u32_e32 v55, vcc, 0, v11, vcc
	v_add_co_u32_e32 v56, vcc, s34, v10
	s_nop 1
	v_addc_co_u32_e32 v57, vcc, 0, v11, vcc
	v_add_co_u32_e32 v58, vcc, s35, v10
	s_nop 1
	v_addc_co_u32_e32 v59, vcc, 0, v11, vcc
	v_add_co_u32_e32 v60, vcc, s36, v10
	s_nop 1
	v_addc_co_u32_e32 v61, vcc, 0, v11, vcc
	v_add_co_u32_e32 v62, vcc, s37, v10
	s_nop 1
	v_addc_co_u32_e32 v63, vcc, 0, v11, vcc
	v_add_co_u32_e32 v64, vcc, s38, v10
	s_nop 1
	v_addc_co_u32_e32 v65, vcc, 0, v11, vcc
	v_add_co_u32_e32 v66, vcc, s39, v10
	s_nop 1
	v_addc_co_u32_e32 v67, vcc, 0, v11, vcc
	v_add_co_u32_e32 v68, vcc, s40, v10
	s_nop 1
	v_addc_co_u32_e32 v69, vcc, 0, v11, vcc
	v_add_co_u32_e32 v70, vcc, s41, v10
	s_nop 1
	v_addc_co_u32_e32 v71, vcc, 0, v11, vcc
	v_add_co_u32_e32 v72, vcc, s42, v10
	s_nop 1
	v_addc_co_u32_e32 v73, vcc, 0, v11, vcc
	v_add_co_u32_e32 v74, vcc, s43, v10
	s_nop 1
	v_addc_co_u32_e32 v75, vcc, 0, v11, vcc
	v_add_co_u32_e32 v76, vcc, s46, v10
	s_nop 1
	v_addc_co_u32_e32 v77, vcc, 0, v11, vcc
	v_add_co_u32_e32 v78, vcc, s47, v10
	s_nop 1
	v_addc_co_u32_e32 v79, vcc, 0, v11, vcc
	v_add_co_u32_e32 v80, vcc, s48, v10
	s_nop 1
	v_addc_co_u32_e32 v81, vcc, 0, v11, vcc
	global_load_dword v6, v[10:11], off nt
	global_load_dword v13, v[16:17], off nt
	global_load_dword v82, v[18:19], off nt
	global_load_dword v83, v[20:21], off nt
	global_load_dword v84, v[22:23], off nt
	s_nop 0
	global_load_dword v24, v[24:25], off nt
	s_nop 0
	global_load_dword v25, v[26:27], off nt
	s_nop 0
	global_load_dword v26, v[28:29], off nt
	global_load_dword v27, v[30:31], off nt
	s_nop 0
	global_load_dword v28, v[32:33], off nt
	global_load_dword v29, v[34:35], off nt
	global_load_dword v30, v[36:37], off nt
	global_load_dword v31, v[38:39], off nt
	s_nop 0
	global_load_dword v32, v[40:41], off nt
	global_load_dword v33, v[42:43], off nt
	global_load_dword v34, v[44:45], off nt
	global_load_dword v35, v[50:51], off nt
	global_load_dword v36, v[52:53], off nt
	global_load_dword v37, v[54:55], off nt
	global_load_dword v38, v[56:57], off nt
	global_load_dword v39, v[58:59], off nt
	global_load_dword v40, v[60:61], off nt
	global_load_dword v41, v[62:63], off nt
	global_load_dword v42, v[64:65], off nt
	global_load_dword v43, v[66:67], off nt
	global_load_dword v44, v[68:69], off nt
	global_load_dword v45, v[70:71], off nt
	global_load_dword v50, v[72:73], off nt
	global_load_dword v51, v[74:75], off nt
	global_load_dword v52, v[76:77], off nt
	global_load_dword v53, v[78:79], off nt
	global_load_dword v54, v[80:81], off nt
	v_lshl_add_u64 v[16:17], v[8:9], 1, v[2:3]
	v_add_u32_e32 v8, 8, v14
	v_add_u32_e32 v55, 0x400, v12
	v_add_u32_e32 v56, 0x800, v12
	v_add_u32_e32 v57, 0xc00, v12
	v_add_u32_e32 v58, 0x1000, v12
	v_add_u32_e32 v59, 0x1400, v12
	v_add_u32_e32 v60, 0x1800, v12
	v_add_u32_e32 v61, 0x1c00, v12
	v_add_u32_e32 v10, 16, v14
	v_ashrrev_i32_e32 v9, 31, v8
	s_waitcnt vmcnt(30)
	ds_write2_b32 v12, v6, v13 offset1:66
	s_waitcnt vmcnt(28)
	ds_write2_b32 v12, v82, v83 offset0:132 offset1:198
	s_waitcnt vmcnt(26)
	ds_write2_b32 v55, v84, v24 offset0:8 offset1:74
	s_waitcnt vmcnt(24)
	ds_write2_b32 v55, v25, v26 offset0:140 offset1:206
	s_waitcnt vmcnt(22)
	ds_write2_b32 v56, v27, v28 offset0:16 offset1:82
	s_waitcnt vmcnt(20)
	ds_write2_b32 v56, v29, v30 offset0:148 offset1:214
	s_waitcnt vmcnt(18)
	ds_write2_b32 v57, v31, v32 offset0:24 offset1:90
	s_waitcnt vmcnt(16)
	ds_write2_b32 v57, v33, v34 offset0:156 offset1:222
	s_waitcnt vmcnt(14)
	ds_write2_b32 v58, v35, v36 offset0:32 offset1:98
	s_waitcnt vmcnt(12)
	ds_write2_b32 v58, v37, v38 offset0:164 offset1:230
	s_waitcnt vmcnt(10)
	ds_write2_b32 v59, v39, v40 offset0:40 offset1:106
	s_waitcnt vmcnt(8)
	ds_write2_b32 v59, v41, v42 offset0:172 offset1:238
	s_waitcnt vmcnt(6)
	ds_write2_b32 v60, v43, v44 offset0:48 offset1:114
	s_waitcnt vmcnt(4)
	ds_write2_b32 v60, v45, v50 offset0:180 offset1:246
	s_waitcnt vmcnt(2)
	ds_write2_b32 v61, v51, v52 offset0:56 offset1:122
	s_waitcnt vmcnt(0)
	ds_write2_b32 v61, v53, v54 offset0:188 offset1:254
	v_ashrrev_i32_e32 v11, 31, v10
	v_lshlrev_b64 v[8:9], 12, v[8:9]
	s_waitcnt lgkmcnt(0)
	v_lshlrev_b64 v[10:11], 12, v[10:11]
	v_lshl_add_u64 v[20:21], v[16:17], 0, v[8:9]
	ds_read2_b32 v[8:9], v7 offset1:33
	v_lshl_add_u64 v[22:23], v[16:17], 0, v[10:11]
	s_waitcnt lgkmcnt(0)
	v_cvt_pk_bf16_f32 v8, v8, v9
	ds_read2_b32 v[10:11], v7 offset0:66 offset1:99
	v_lshlrev_b64 v[18:19], 12, v[14:15]
	s_waitcnt lgkmcnt(0)
	v_cvt_pk_bf16_f32 v9, v10, v11
	ds_read2_b32 v[10:11], v7 offset0:132 offset1:165
	v_lshl_add_u64 v[18:19], v[16:17], 0, v[18:19]
	s_waitcnt lgkmcnt(0)
	v_cvt_pk_bf16_f32 v10, v10, v11
	ds_read2_b32 v[24:25], v7 offset0:198 offset1:231
	s_waitcnt lgkmcnt(0)
	v_cvt_pk_bf16_f32 v11, v24, v25
	ds_read2_b32 v[24:25], v7 offset0:8 offset1:41
	global_store_dwordx4 v[18:19], v[8:11], off nt
	v_add_u32_e32 v14, 24, v14
	v_ashrrev_i32_e32 v15, 31, v14
	s_waitcnt lgkmcnt(0)
	v_cvt_pk_bf16_f32 v8, v24, v25
	ds_read2_b32 v[10:11], v7 offset0:74 offset1:107
	s_waitcnt lgkmcnt(0)
	v_cvt_pk_bf16_f32 v9, v10, v11
	ds_read2_b32 v[10:11], v7 offset0:140 offset1:173
	s_waitcnt lgkmcnt(0)
	v_cvt_pk_bf16_f32 v10, v10, v11
	ds_read2_b32 v[18:19], v7 offset0:206 offset1:239
	s_waitcnt lgkmcnt(0)
	v_cvt_pk_bf16_f32 v11, v18, v19
	ds_read2_b32 v[18:19], v7 offset0:16 offset1:49
	global_store_dwordx4 v[20:21], v[8:11], off nt
	v_lshlrev_b64 v[14:15], 12, v[14:15]
	v_lshl_add_u64 v[14:15], v[16:17], 0, v[14:15]
	s_waitcnt lgkmcnt(0)
	v_cvt_pk_bf16_f32 v8, v18, v19
	ds_read2_b32 v[10:11], v7 offset0:82 offset1:115
	s_waitcnt lgkmcnt(0)
	v_cvt_pk_bf16_f32 v9, v10, v11
	ds_read2_b32 v[10:11], v7 offset0:148 offset1:181
	s_waitcnt lgkmcnt(0)
	v_cvt_pk_bf16_f32 v10, v10, v11
	ds_read2_b32 v[18:19], v7 offset0:214 offset1:247
	s_waitcnt lgkmcnt(0)
	v_cvt_pk_bf16_f32 v11, v18, v19
	ds_read2_b32 v[18:19], v7 offset0:24 offset1:57
	global_store_dwordx4 v[22:23], v[8:11], off nt
	v_cmp_lt_i32_e32 vcc, s49, v46
	s_or_b64 s[2:3], vcc, s[2:3]
	s_waitcnt lgkmcnt(0)
	v_cvt_pk_bf16_f32 v8, v18, v19
	ds_read2_b32 v[10:11], v7 offset0:90 offset1:123
	s_waitcnt lgkmcnt(0)
	v_cvt_pk_bf16_f32 v9, v10, v11
	ds_read2_b32 v[10:11], v7 offset0:156 offset1:189
	s_waitcnt lgkmcnt(0)
	v_cvt_pk_bf16_f32 v10, v10, v11
	ds_read2_b32 v[18:19], v7 offset0:222 offset1:255
	s_waitcnt lgkmcnt(0)
	v_cvt_pk_bf16_f32 v11, v18, v19
	global_store_dwordx4 v[14:15], v[8:11], off nt
	s_waitcnt lgkmcnt(0)
	s_andn2_b64 exec, exec, s[2:3]
	s_cbranch_execnz .LBB0_121
